# merge gate GEMM (K=1024) K loop also on the hand-written HBM->LDS DMA loop
# speedup vs baseline: 1.1066x; 1.0242x over previous
; DEV int tid_() { int t = threadIdx.x; asm volatile("" : "+v"(t)); return t; }
; template <int NI, bool DEEP = true>
; DEV void gemm_tile(f32x16 (&acc)[2][NI], const bf16* __restrict__ A, int lda, const bf16* __restrict__ Bt, int ldb,
;                    int K, bf16* sA, bf16* sB) {
;   int tid = tid_(), lane = tid & 63, wave = tid >> 6;
;   int wm = wave >> 1, wn = wave & 1;
;   int lr = tid >> 3, lc = (tid & 7) * 8;
;   const bf16* Ap = A + (size_t)lr * lda + lc;
;   const bf16* Bp = Bt + (size_t)lr * ldb + lc;
;   u32x4 ra0[4], rb0[2 * NI], ra1[4], rb1[2 * NI];
; __device__ void phase_merge(PRef p, int l, const bf16* H2, bf16* M, bf16* sA, bf16* sB) {
;     ...
;     for (int n = 0; n < 3; n++) {
;       const bf16* U = n == 0 ? p.HY : (n == 1 ? p.ZB : p.ZC);
;       int ldu = n == 2 ? 768 : 512;
;       uint32_t gp[2][2][8];
;       {
;         f32x16 a2[2][2];
;         zero_acc<2>(a2);
;         gemm_tile<2>(a2, H2 + (size_t)rt * 128 * 1024, 1024, p.WT3 + ((size_t)n * 1024 + ct * 128) * 1024, 1024, 1024, sA, sB);
.LBB0_962:
	s_load_dwordx2 s[54:55], s[34:35], 0x0
	s_lshl_b32 s0, s95, 10
	s_add_u32 s56, s0, s20
	s_addc_u32 s57, 0, s21
	s_lshl_b64 s[0:1], s[56:57], 11
	s_add_u32 s100, s4, s0
	s_addc_u32 s101, s5, s1
	s_mov_b64 s[98:99], s[16:17]
	v_and_b32_e32 v0, 63, v196
	v_lshrrev_b32_e32 v1, 6, v196
	v_lshrrev_b32_e32 v2, 3, v0
	v_readfirstlane_b32 s0, v1
	v_lshrrev_b32_e32 v30, 1, v2
	v_and_b32_e32 v31, 7, v0
	v_xor_b32_e32 v30, v31, v30
	v_lshlrev_b32_e32 v30, 4, v30
	v_lshl_or_b32 v20, v2, 11, v30
	v_xor_b32_e32 v21, 64, v20
	v_lshrrev_b32_e32 v30, 5, v0
	v_bfe_u32 v31, v0, 1, 3
	v_and_b32_e32 v2, 31, v0
	v_lshrrev_b32_e32 v0, 1, v1
	v_and_b32_e32 v1, 1, v1
	v_lshl_add_u32 v0, v0, 6, v2
	v_lshl_add_u32 v1, v1, 6, v2
	v_lshlrev_b32_e32 v0, 7, v0
	v_lshlrev_b32_e32 v1, 7, v1
	v_add_u32_e32 v1, 0x4000, v1
	v_add_u32_e32 v2, 0, v30
	v_xor_b32_e32 v2, v2, v31
	v_lshl_add_u32 v22, v2, 4, v0
	v_lshl_add_u32 v26, v2, 4, v1
	v_add_u32_e32 v2, 2, v30
	v_xor_b32_e32 v2, v2, v31
	v_lshl_add_u32 v23, v2, 4, v0
	v_lshl_add_u32 v27, v2, 4, v1
	v_add_u32_e32 v2, 4, v30
	v_xor_b32_e32 v2, v2, v31
	v_lshl_add_u32 v24, v2, 4, v0
	v_lshl_add_u32 v28, v2, 4, v1
	v_add_u32_e32 v2, 6, v30
	v_xor_b32_e32 v2, v2, v31
	v_lshl_add_u32 v25, v2, 4, v0
	v_lshl_add_u32 v29, v2, 4, v1
	s_lshl_b32 s1, s0, 16
	s_lshl_b32 s0, s0, 12
	s_add_u32 s98, s98, s1
	s_addc_u32 s99, s99, 0
	s_add_u32 s100, s100, s1
	s_addc_u32 s101, s101, 0
	s_waitcnt lgkmcnt(0)
	s_barrier
	s_add_u32 m0, s0, 0x0
	s_nop 0
	global_load_lds_dwordx4 v20, s[98:99]
	s_add_u32 m0, s0, 0x400
	s_add_u32 s34, s98, 0x4000
	s_addc_u32 s35, s99, 0
	global_load_lds_dwordx4 v21, s[34:35]
	s_add_u32 m0, s0, 0x800
	s_add_u32 s34, s98, 0x8000
	s_addc_u32 s35, s99, 0
	global_load_lds_dwordx4 v20, s[34:35]
	s_add_u32 m0, s0, 0xc00
	s_add_u32 s34, s98, 0xc000
	s_addc_u32 s35, s99, 0
	global_load_lds_dwordx4 v21, s[34:35]
	s_add_u32 m0, s0, 0x4000
	s_nop 0
	global_load_lds_dwordx4 v20, s[100:101]
	s_add_u32 m0, s0, 0x4400
	s_add_u32 s34, s100, 0x4000
	s_addc_u32 s35, s101, 0
	global_load_lds_dwordx4 v21, s[34:35]
	s_add_u32 m0, s0, 0x4800
	s_add_u32 s34, s100, 0x8000
	s_addc_u32 s35, s101, 0
	global_load_lds_dwordx4 v20, s[34:35]
	s_add_u32 m0, s0, 0x4c00
	s_add_u32 s34, s100, 0xc000
	s_addc_u32 s35, s101, 0
	global_load_lds_dwordx4 v21, s[34:35]
	s_add_u32 s98, s98, 0x80
	s_addc_u32 s99, s99, 0
	s_add_u32 s100, s100, 0x80
	s_addc_u32 s101, s101, 0
	v_mov_b32_e32 v4, 0
	v_mov_b32_e32 v5, 0
	v_mov_b32_e32 v6, 0
	v_mov_b32_e32 v7, 0
	v_mov_b32_e32 v8, 0
	v_mov_b32_e32 v9, 0
	v_mov_b32_e32 v10, 0
	v_mov_b32_e32 v11, 0
	v_mov_b32_e32 v12, 0
	v_mov_b32_e32 v13, 0
	v_mov_b32_e32 v14, 0
	v_mov_b32_e32 v15, 0
	v_mov_b32_e32 v16, 0
	v_mov_b32_e32 v17, 0
	v_mov_b32_e32 v18, 0
	v_mov_b32_e32 v19, 0
	v_mov_b32_e32 v68, 0
	v_mov_b32_e32 v69, 0
	v_mov_b32_e32 v70, 0
	v_mov_b32_e32 v71, 0
	v_mov_b32_e32 v72, 0
	v_mov_b32_e32 v73, 0
	v_mov_b32_e32 v74, 0
	v_mov_b32_e32 v75, 0
	v_mov_b32_e32 v76, 0
	v_mov_b32_e32 v77, 0
	v_mov_b32_e32 v78, 0
	v_mov_b32_e32 v79, 0
	v_mov_b32_e32 v80, 0
	v_mov_b32_e32 v81, 0
	v_mov_b32_e32 v82, 0
	v_mov_b32_e32 v83, 0
	v_mov_b32_e32 v100, 0
	v_mov_b32_e32 v101, 0
	v_mov_b32_e32 v102, 0
	v_mov_b32_e32 v103, 0
	v_mov_b32_e32 v104, 0
	v_mov_b32_e32 v105, 0
	v_mov_b32_e32 v106, 0
	v_mov_b32_e32 v107, 0
	v_mov_b32_e32 v108, 0
	v_mov_b32_e32 v109, 0
	v_mov_b32_e32 v110, 0
	v_mov_b32_e32 v111, 0
	v_mov_b32_e32 v112, 0
	v_mov_b32_e32 v113, 0
	v_mov_b32_e32 v114, 0
	v_mov_b32_e32 v115, 0
	v_mov_b32_e32 v116, 0
	v_mov_b32_e32 v117, 0
	v_mov_b32_e32 v118, 0
	v_mov_b32_e32 v119, 0
	v_mov_b32_e32 v120, 0
	v_mov_b32_e32 v121, 0
	v_mov_b32_e32 v122, 0
	v_mov_b32_e32 v123, 0
	v_mov_b32_e32 v124, 0
	v_mov_b32_e32 v125, 0
	v_mov_b32_e32 v126, 0
	v_mov_b32_e32 v127, 0
	v_mov_b32_e32 v128, 0
	v_mov_b32_e32 v129, 0
	v_mov_b32_e32 v130, 0
	v_mov_b32_e32 v131, 0
	s_mov_b32 s28, 0
; template <int NI, bool DEEP = true>
; DEV void gemm_tile(f32x16 (&acc)[2][NI], const bf16* __restrict__ A, int lda, const bf16* __restrict__ Bt, int ldb,
;                    int K, bf16* sA, bf16* sB) {
;     ...
;   G_LOAD(ra0, rb0, 0)
;   if (DEEP) {
;     if (64 < K) G_LOAD(ra1, rb1, 64)
;     for (int k0 = 0; k0 < K; k0 += 128) {
;       G_STEP(ra0, rb0, k0 + 128)
;       if (k0 + 64 < K) G_STEP(ra1, rb1, k0 + 192)
;     }
.Lmak_loop:
	s_waitcnt vmcnt(0)
	s_barrier
	s_add_u32 m0, s0, 0x8000
	s_nop 0
	global_load_lds_dwordx4 v20, s[98:99]
	s_add_u32 m0, s0, 0x8400
	s_add_u32 s34, s98, 0x4000
	s_addc_u32 s35, s99, 0
	global_load_lds_dwordx4 v21, s[34:35]
	s_add_u32 m0, s0, 0x8800
	s_add_u32 s34, s98, 0x8000
	s_addc_u32 s35, s99, 0
	global_load_lds_dwordx4 v20, s[34:35]
	s_add_u32 m0, s0, 0x8c00
	s_add_u32 s34, s98, 0xc000
	s_addc_u32 s35, s99, 0
	global_load_lds_dwordx4 v21, s[34:35]
	s_add_u32 m0, s0, 0xd840
	s_nop 0
	global_load_lds_dwordx4 v20, s[100:101]
	s_add_u32 m0, s0, 0xdc40
	s_add_u32 s34, s100, 0x4000
	s_addc_u32 s35, s101, 0
	global_load_lds_dwordx4 v21, s[34:35]
	s_add_u32 m0, s0, 0xe040
	s_add_u32 s34, s100, 0x8000
	s_addc_u32 s35, s101, 0
	global_load_lds_dwordx4 v20, s[34:35]
	s_add_u32 m0, s0, 0xe440
	s_add_u32 s34, s100, 0xc000
	s_addc_u32 s35, s101, 0
	global_load_lds_dwordx4 v21, s[34:35]
	s_add_u32 s98, s98, 0x80
	s_addc_u32 s99, s99, 0
	s_add_u32 s100, s100, 0x80
	s_addc_u32 s101, s101, 0
	ds_read_b128 v[40:43], v26 offset:0
	ds_read_b128 v[32:35], v22 offset:0
	ds_read_b128 v[36:39], v22 offset:4096
	ds_read_b128 v[44:47], v26 offset:4096
	s_waitcnt lgkmcnt(2)
	v_mfma_f32_32x32x16_bf16 v[116:131], v[40:43], v[32:35], v[116:131]
	ds_read_b128 v[56:59], v27 offset:0
	ds_read_b128 v[48:51], v23 offset:0
	s_waitcnt lgkmcnt(3)
	v_mfma_f32_32x32x16_bf16 v[68:83], v[40:43], v[36:39], v[68:83]
	ds_read_b128 v[52:55], v23 offset:4096
	s_waitcnt lgkmcnt(3)
	v_mfma_f32_32x32x16_bf16 v[100:115], v[44:47], v[32:35], v[100:115]
	ds_read_b128 v[60:63], v27 offset:4096
	v_mfma_f32_32x32x16_bf16 v[4:19], v[44:47], v[36:39], v[4:19]
	s_waitcnt lgkmcnt(2)
	v_mfma_f32_32x32x16_bf16 v[116:131], v[56:59], v[48:51], v[116:131]
	ds_read_b128 v[40:43], v28 offset:0
	ds_read_b128 v[32:35], v24 offset:0
	s_waitcnt lgkmcnt(3)
	v_mfma_f32_32x32x16_bf16 v[68:83], v[56:59], v[52:55], v[68:83]
	ds_read_b128 v[36:39], v24 offset:4096
	s_waitcnt lgkmcnt(3)
	v_mfma_f32_32x32x16_bf16 v[100:115], v[60:63], v[48:51], v[100:115]
	ds_read_b128 v[44:47], v28 offset:4096
	v_mfma_f32_32x32x16_bf16 v[4:19], v[60:63], v[52:55], v[4:19]
	s_waitcnt lgkmcnt(2)
	v_mfma_f32_32x32x16_bf16 v[116:131], v[40:43], v[32:35], v[116:131]
	ds_read_b128 v[56:59], v29 offset:0
	ds_read_b128 v[48:51], v25 offset:0
	s_waitcnt lgkmcnt(3)
	v_mfma_f32_32x32x16_bf16 v[68:83], v[40:43], v[36:39], v[68:83]
	ds_read_b128 v[52:55], v25 offset:4096
	s_waitcnt lgkmcnt(3)
	v_mfma_f32_32x32x16_bf16 v[100:115], v[44:47], v[32:35], v[100:115]
	ds_read_b128 v[60:63], v29 offset:4096
	v_mfma_f32_32x32x16_bf16 v[4:19], v[44:47], v[36:39], v[4:19]
	s_waitcnt lgkmcnt(2)
	v_mfma_f32_32x32x16_bf16 v[116:131], v[56:59], v[48:51], v[116:131]
	s_waitcnt lgkmcnt(1)
	v_mfma_f32_32x32x16_bf16 v[68:83], v[56:59], v[52:55], v[68:83]
	s_waitcnt lgkmcnt(0)
	v_mfma_f32_32x32x16_bf16 v[100:115], v[60:63], v[48:51], v[100:115]
	v_mfma_f32_32x32x16_bf16 v[4:19], v[60:63], v[52:55], v[4:19]
	s_waitcnt vmcnt(0)
	s_barrier
	s_cmp_eq_u32 s28, 7
	s_cbranch_scc1 .Lmak_nodma
	s_add_u32 m0, s0, 0x0
	s_nop 0
	global_load_lds_dwordx4 v20, s[98:99]
	s_add_u32 m0, s0, 0x400
	s_add_u32 s34, s98, 0x4000
	s_addc_u32 s35, s99, 0
	global_load_lds_dwordx4 v21, s[34:35]
	s_add_u32 m0, s0, 0x800
	s_add_u32 s34, s98, 0x8000
	s_addc_u32 s35, s99, 0
	global_load_lds_dwordx4 v20, s[34:35]
	s_add_u32 m0, s0, 0xc00
	s_add_u32 s34, s98, 0xc000
	s_addc_u32 s35, s99, 0
	global_load_lds_dwordx4 v21, s[34:35]
	s_add_u32 m0, s0, 0x4000
	s_nop 0
	global_load_lds_dwordx4 v20, s[100:101]
	s_add_u32 m0, s0, 0x4400
	s_add_u32 s34, s100, 0x4000
	s_addc_u32 s35, s101, 0
	global_load_lds_dwordx4 v21, s[34:35]
	s_add_u32 m0, s0, 0x4800
	s_add_u32 s34, s100, 0x8000
	s_addc_u32 s35, s101, 0
	global_load_lds_dwordx4 v20, s[34:35]
	s_add_u32 m0, s0, 0x4c00
	s_add_u32 s34, s100, 0xc000
	s_addc_u32 s35, s101, 0
	global_load_lds_dwordx4 v21, s[34:35]
	s_add_u32 s98, s98, 0x80
	s_addc_u32 s99, s99, 0
	s_add_u32 s100, s100, 0x80
	s_addc_u32 s101, s101, 0
.Lmak_nodma:
	ds_read_b128 v[40:43], v26 offset:38976
	ds_read_b128 v[32:35], v22 offset:32768
	ds_read_b128 v[36:39], v22 offset:36864
	ds_read_b128 v[44:47], v26 offset:43072
	s_waitcnt lgkmcnt(2)
	v_mfma_f32_32x32x16_bf16 v[116:131], v[40:43], v[32:35], v[116:131]
	ds_read_b128 v[56:59], v27 offset:38976
	ds_read_b128 v[48:51], v23 offset:32768
	s_waitcnt lgkmcnt(3)
	v_mfma_f32_32x32x16_bf16 v[68:83], v[40:43], v[36:39], v[68:83]
	ds_read_b128 v[52:55], v23 offset:36864
	s_waitcnt lgkmcnt(3)
	v_mfma_f32_32x32x16_bf16 v[100:115], v[44:47], v[32:35], v[100:115]
	ds_read_b128 v[60:63], v27 offset:43072
	v_mfma_f32_32x32x16_bf16 v[4:19], v[44:47], v[36:39], v[4:19]
	s_waitcnt lgkmcnt(2)
	v_mfma_f32_32x32x16_bf16 v[116:131], v[56:59], v[48:51], v[116:131]
	ds_read_b128 v[40:43], v28 offset:38976
	ds_read_b128 v[32:35], v24 offset:32768
	s_waitcnt lgkmcnt(3)
	v_mfma_f32_32x32x16_bf16 v[68:83], v[56:59], v[52:55], v[68:83]
	ds_read_b128 v[36:39], v24 offset:36864
	s_waitcnt lgkmcnt(3)
	v_mfma_f32_32x32x16_bf16 v[100:115], v[60:63], v[48:51], v[100:115]
	ds_read_b128 v[44:47], v28 offset:43072
	v_mfma_f32_32x32x16_bf16 v[4:19], v[60:63], v[52:55], v[4:19]
	s_waitcnt lgkmcnt(2)
	v_mfma_f32_32x32x16_bf16 v[116:131], v[40:43], v[32:35], v[116:131]
	ds_read_b128 v[56:59], v29 offset:38976
	ds_read_b128 v[48:51], v25 offset:32768
	s_waitcnt lgkmcnt(3)
	v_mfma_f32_32x32x16_bf16 v[68:83], v[40:43], v[36:39], v[68:83]
	ds_read_b128 v[52:55], v25 offset:36864
	s_waitcnt lgkmcnt(3)
	v_mfma_f32_32x32x16_bf16 v[100:115], v[44:47], v[32:35], v[100:115]
	ds_read_b128 v[60:63], v29 offset:43072
	v_mfma_f32_32x32x16_bf16 v[4:19], v[44:47], v[36:39], v[4:19]
	s_waitcnt lgkmcnt(2)
	v_mfma_f32_32x32x16_bf16 v[116:131], v[56:59], v[48:51], v[116:131]
	s_waitcnt lgkmcnt(1)
	v_mfma_f32_32x32x16_bf16 v[68:83], v[56:59], v[52:55], v[68:83]
	s_waitcnt lgkmcnt(0)
	v_mfma_f32_32x32x16_bf16 v[100:115], v[60:63], v[48:51], v[100:115]
	v_mfma_f32_32x32x16_bf16 v[4:19], v[60:63], v[52:55], v[4:19]
	s_add_i32 s28, s28, 1
	s_cmp_lt_u32 s28, 8
	s_cbranch_scc1 .Lmak_loop
	s_nop 7
	s_nop 7
